# write-through sc1 stores in split-K partial epilogues P5 and P9
# speedup vs baseline: 1.0141x; 1.0141x over previous
.LBB0_1052:
	s_cmp_eq_u32 s38, 0
	s_cselect_b32 s2, s52, 0xd000000
	s_add_u32 s2, s74, s2
	s_addc_u32 s3, s75, 0
	s_lshl_b32 s13, s30, 8
	v_add_u32_e32 v154, s13, v142
	v_ashrrev_i32_e32 v155, 31, v154
	s_lshl_b32 s20, s20, 8
	v_lshlrev_b64 v[154:155], 11, v[154:155]
	s_ashr_i32 s21, s20, 31
	v_lshl_add_u64 v[154:155], s[2:3], 0, v[154:155]
	s_lshl_b64 s[20:21], s[20:21], 1
	v_cvt_pk_bf16_f32 v124, v124, v125
	v_cvt_pk_bf16_f32 v125, v126, v127
	v_cvt_pk_bf16_f32 v126, v120, v121
	v_lshl_add_u64 v[120:121], v[154:155], 0, s[20:21]
	v_lshl_add_u64 v[120:121], v[120:121], 0, s[4:5]
	v_lshl_add_u64 v[120:121], v[120:121], 0, v[136:137]
	v_cvt_pk_bf16_f32 v127, v122, v123
	global_store_dwordx4 v[120:121], v[124:127], off sc1
	v_cvt_pk_bf16_f32 v112, v112, v113
	v_cvt_pk_bf16_f32 v113, v114, v115
	v_cvt_pk_bf16_f32 v114, v104, v105
	v_add_u32_e32 v104, s13, v144
	v_ashrrev_i32_e32 v105, 31, v104
	v_lshlrev_b64 v[104:105], 11, v[104:105]
	v_cvt_pk_bf16_f32 v115, v106, v107
	global_store_dwordx4 v[120:121], v[112:115], off offset:256 sc1
	s_and_b64 vcc, exec, s[0:1]
	s_mov_b64 s[0:1], -1
	v_lshl_add_u64 v[112:113], s[2:3], 0, v[104:105]
	v_cvt_pk_bf16_f32 v104, v116, v117
	v_cvt_pk_bf16_f32 v105, v118, v119
	v_cvt_pk_bf16_f32 v106, v108, v109
	v_lshl_add_u64 v[108:109], v[112:113], 0, s[20:21]
	v_lshl_add_u64 v[108:109], v[108:109], 0, s[4:5]
	v_lshl_add_u64 v[108:109], v[108:109], 0, v[136:137]
	v_cvt_pk_bf16_f32 v107, v110, v111
	global_store_dwordx4 v[108:109], v[104:107], off sc1
	v_cvt_pk_bf16_f32 v96, v96, v97
	v_cvt_pk_bf16_f32 v97, v98, v99
	v_cvt_pk_bf16_f32 v98, v88, v89
	v_add_u32_e32 v88, s13, v145
	v_ashrrev_i32_e32 v89, 31, v88
	v_lshlrev_b64 v[88:89], 11, v[88:89]
	v_cvt_pk_bf16_f32 v99, v90, v91
	global_store_dwordx4 v[108:109], v[96:99], off offset:256 sc1
	s_nop 1
	v_lshl_add_u64 v[96:97], s[2:3], 0, v[88:89]
	v_cvt_pk_bf16_f32 v88, v100, v101
	v_cvt_pk_bf16_f32 v89, v102, v103
	v_cvt_pk_bf16_f32 v90, v92, v93
	v_lshl_add_u64 v[92:93], v[96:97], 0, s[20:21]
	v_lshl_add_u64 v[92:93], v[92:93], 0, s[4:5]
	v_lshl_add_u64 v[92:93], v[92:93], 0, v[136:137]
	v_cvt_pk_bf16_f32 v91, v94, v95
	global_store_dwordx4 v[92:93], v[88:91], off sc1
	v_cvt_pk_bf16_f32 v80, v80, v81
	v_cvt_pk_bf16_f32 v81, v82, v83
	v_cvt_pk_bf16_f32 v82, v72, v73
	v_add_u32_e32 v72, s13, v146
	v_ashrrev_i32_e32 v73, 31, v72
	v_lshlrev_b64 v[72:73], 11, v[72:73]
	v_cvt_pk_bf16_f32 v83, v74, v75
	global_store_dwordx4 v[92:93], v[80:83], off offset:256 sc1
	s_nop 1
	v_lshl_add_u64 v[80:81], s[2:3], 0, v[72:73]
	v_cvt_pk_bf16_f32 v72, v84, v85
	v_cvt_pk_bf16_f32 v73, v86, v87
	v_cvt_pk_bf16_f32 v74, v76, v77
	v_lshl_add_u64 v[76:77], v[80:81], 0, s[20:21]
	v_lshl_add_u64 v[76:77], v[76:77], 0, s[4:5]
	v_lshl_add_u64 v[76:77], v[76:77], 0, v[136:137]
	v_cvt_pk_bf16_f32 v75, v78, v79
	global_store_dwordx4 v[76:77], v[72:75], off sc1
	v_cvt_pk_bf16_f32 v68, v68, v69
	v_cvt_pk_bf16_f32 v69, v70, v71
	v_cvt_pk_bf16_f32 v70, v64, v65
	v_add_u32_e32 v64, s13, v147
	v_ashrrev_i32_e32 v65, 31, v64
	v_lshlrev_b64 v[64:65], 11, v[64:65]
	v_lshl_add_u64 v[64:65], s[2:3], 0, v[64:65]
	v_cvt_pk_bf16_f32 v71, v66, v67
	global_store_dwordx4 v[76:77], v[68:71], off offset:256 sc1
	v_cvt_pk_bf16_f32 v60, v60, v61
	v_cvt_pk_bf16_f32 v61, v62, v63
	v_cvt_pk_bf16_f32 v62, v56, v57
	v_lshl_add_u64 v[56:57], v[64:65], 0, s[20:21]
	v_lshl_add_u64 v[56:57], v[56:57], 0, s[4:5]
	v_lshl_add_u64 v[56:57], v[56:57], 0, v[136:137]
	v_cvt_pk_bf16_f32 v63, v58, v59
	global_store_dwordx4 v[56:57], v[60:63], off sc1
	v_cvt_pk_bf16_f32 v48, v48, v49
	v_cvt_pk_bf16_f32 v49, v50, v51
	v_cvt_pk_bf16_f32 v50, v40, v41
	v_add_u32_e32 v40, s13, v148
	v_ashrrev_i32_e32 v41, 31, v40
	v_lshlrev_b64 v[40:41], 11, v[40:41]
	v_cvt_pk_bf16_f32 v51, v42, v43
	global_store_dwordx4 v[56:57], v[48:51], off offset:256 sc1
	s_nop 1
	v_lshl_add_u64 v[48:49], s[2:3], 0, v[40:41]
	v_cvt_pk_bf16_f32 v40, v52, v53
	v_cvt_pk_bf16_f32 v41, v54, v55
	v_cvt_pk_bf16_f32 v42, v44, v45
	v_lshl_add_u64 v[44:45], v[48:49], 0, s[20:21]
	v_lshl_add_u64 v[44:45], v[44:45], 0, s[4:5]
	v_lshl_add_u64 v[44:45], v[44:45], 0, v[136:137]
	v_cvt_pk_bf16_f32 v43, v46, v47
	global_store_dwordx4 v[44:45], v[40:43], off sc1
	v_cvt_pk_bf16_f32 v32, v32, v33
	v_cvt_pk_bf16_f32 v33, v34, v35
	v_cvt_pk_bf16_f32 v34, v24, v25
	v_add_u32_e32 v24, s13, v149
	v_ashrrev_i32_e32 v25, 31, v24
	v_lshlrev_b64 v[24:25], 11, v[24:25]
	v_cvt_pk_bf16_f32 v35, v26, v27
	global_store_dwordx4 v[44:45], v[32:35], off offset:256 sc1
	s_nop 1
	v_lshl_add_u64 v[32:33], s[2:3], 0, v[24:25]
	v_cvt_pk_bf16_f32 v24, v36, v37
	v_cvt_pk_bf16_f32 v25, v38, v39
	v_cvt_pk_bf16_f32 v26, v28, v29
	v_lshl_add_u64 v[28:29], v[32:33], 0, s[20:21]
	v_lshl_add_u64 v[28:29], v[28:29], 0, s[4:5]
	v_lshl_add_u64 v[28:29], v[28:29], 0, v[136:137]
	v_cvt_pk_bf16_f32 v27, v30, v31
	global_store_dwordx4 v[28:29], v[24:27], off sc1
	v_cvt_pk_bf16_f32 v16, v16, v17
	v_cvt_pk_bf16_f32 v17, v18, v19
	v_cvt_pk_bf16_f32 v18, v8, v9
	v_add_u32_e32 v8, s13, v150
	v_ashrrev_i32_e32 v9, 31, v8
	v_lshlrev_b64 v[8:9], 11, v[8:9]
	v_cvt_pk_bf16_f32 v19, v10, v11
	global_store_dwordx4 v[28:29], v[16:19], off offset:256 sc1
	s_nop 1
	v_lshl_add_u64 v[16:17], s[2:3], 0, v[8:9]
	v_cvt_pk_bf16_f32 v8, v20, v21
	v_cvt_pk_bf16_f32 v9, v22, v23
	v_cvt_pk_bf16_f32 v10, v12, v13
	v_lshl_add_u64 v[12:13], v[16:17], 0, s[20:21]
	v_lshl_add_u64 v[12:13], v[12:13], 0, s[4:5]
	v_lshl_add_u64 v[12:13], v[12:13], 0, v[136:137]
	v_cvt_pk_bf16_f32 v11, v14, v15
	global_store_dwordx4 v[12:13], v[8:11], off sc1
	v_cvt_pk_bf16_f32 v4, v4, v5
	v_cvt_pk_bf16_f32 v5, v6, v7
	v_cvt_pk_bf16_f32 v6, v0, v1
	v_cvt_pk_bf16_f32 v7, v2, v3
	global_store_dwordx4 v[12:13], v[4:7], off offset:256 sc1
	s_cbranch_vccnz .LBB0_1035
	s_andn2_b64 vcc, exec, s[6:7]
	s_cbranch_vccnz .LBB0_1034
	s_barrier
	s_branch .LBB0_1034

.LBB0_1442:
	s_cmp_eq_u32 s18, 0
	s_cselect_b32 s2, s40, 0x5000000
	s_add_u32 s2, s74, s2
	s_addc_u32 s3, s75, 0
	s_lshl_b32 s13, s45, 8
	v_add_u32_e32 v154, s13, v142
	v_ashrrev_i32_e32 v155, 31, v154
	s_lshl_b32 s18, s44, 8
	v_lshlrev_b64 v[154:155], 11, v[154:155]
	s_ashr_i32 s19, s18, 31
	v_lshl_add_u64 v[154:155], s[2:3], 0, v[154:155]
	s_lshl_b64 s[18:19], s[18:19], 1
	v_cvt_pk_bf16_f32 v124, v124, v125
	v_cvt_pk_bf16_f32 v125, v126, v127
	v_cvt_pk_bf16_f32 v126, v120, v121
	v_lshl_add_u64 v[120:121], v[154:155], 0, s[18:19]
	v_lshl_add_u64 v[120:121], v[120:121], 0, s[4:5]
	v_lshl_add_u64 v[120:121], v[120:121], 0, v[136:137]
	v_cvt_pk_bf16_f32 v127, v122, v123
	global_store_dwordx4 v[120:121], v[124:127], off sc1
	v_cvt_pk_bf16_f32 v112, v112, v113
	v_cvt_pk_bf16_f32 v113, v114, v115
	v_cvt_pk_bf16_f32 v114, v104, v105
	v_add_u32_e32 v104, s13, v144
	v_ashrrev_i32_e32 v105, 31, v104
	v_lshlrev_b64 v[104:105], 11, v[104:105]
	v_cvt_pk_bf16_f32 v115, v106, v107
	global_store_dwordx4 v[120:121], v[112:115], off offset:256 sc1
	s_and_b64 vcc, exec, s[0:1]
	s_mov_b64 s[0:1], -1
	v_lshl_add_u64 v[112:113], s[2:3], 0, v[104:105]
	v_cvt_pk_bf16_f32 v104, v116, v117
	v_cvt_pk_bf16_f32 v105, v118, v119
	v_cvt_pk_bf16_f32 v106, v108, v109
	v_lshl_add_u64 v[108:109], v[112:113], 0, s[18:19]
	v_lshl_add_u64 v[108:109], v[108:109], 0, s[4:5]
	v_lshl_add_u64 v[108:109], v[108:109], 0, v[136:137]
	v_cvt_pk_bf16_f32 v107, v110, v111
	global_store_dwordx4 v[108:109], v[104:107], off sc1
	v_cvt_pk_bf16_f32 v96, v96, v97
	v_cvt_pk_bf16_f32 v97, v98, v99
	v_cvt_pk_bf16_f32 v98, v88, v89
	v_add_u32_e32 v88, s13, v145
	v_ashrrev_i32_e32 v89, 31, v88
	v_lshlrev_b64 v[88:89], 11, v[88:89]
	v_cvt_pk_bf16_f32 v99, v90, v91
	global_store_dwordx4 v[108:109], v[96:99], off offset:256 sc1
	s_nop 1
	v_lshl_add_u64 v[96:97], s[2:3], 0, v[88:89]
	v_cvt_pk_bf16_f32 v88, v100, v101
	v_cvt_pk_bf16_f32 v89, v102, v103
	v_cvt_pk_bf16_f32 v90, v92, v93
	v_lshl_add_u64 v[92:93], v[96:97], 0, s[18:19]
	v_lshl_add_u64 v[92:93], v[92:93], 0, s[4:5]
	v_lshl_add_u64 v[92:93], v[92:93], 0, v[136:137]
	v_cvt_pk_bf16_f32 v91, v94, v95
	global_store_dwordx4 v[92:93], v[88:91], off sc1
	v_cvt_pk_bf16_f32 v80, v80, v81
	v_cvt_pk_bf16_f32 v81, v82, v83
	v_cvt_pk_bf16_f32 v82, v72, v73
	v_add_u32_e32 v72, s13, v146
	v_ashrrev_i32_e32 v73, 31, v72
	v_lshlrev_b64 v[72:73], 11, v[72:73]
	v_cvt_pk_bf16_f32 v83, v74, v75
	global_store_dwordx4 v[92:93], v[80:83], off offset:256 sc1
	s_nop 1
	v_lshl_add_u64 v[80:81], s[2:3], 0, v[72:73]
	v_cvt_pk_bf16_f32 v72, v84, v85
	v_cvt_pk_bf16_f32 v73, v86, v87
	v_cvt_pk_bf16_f32 v74, v76, v77
	v_lshl_add_u64 v[76:77], v[80:81], 0, s[18:19]
	v_lshl_add_u64 v[76:77], v[76:77], 0, s[4:5]
	v_lshl_add_u64 v[76:77], v[76:77], 0, v[136:137]
	v_cvt_pk_bf16_f32 v75, v78, v79
	global_store_dwordx4 v[76:77], v[72:75], off sc1
	v_cvt_pk_bf16_f32 v68, v68, v69
	v_cvt_pk_bf16_f32 v69, v70, v71
	v_cvt_pk_bf16_f32 v70, v64, v65
	v_add_u32_e32 v64, s13, v147
	v_ashrrev_i32_e32 v65, 31, v64
	v_lshlrev_b64 v[64:65], 11, v[64:65]
	v_lshl_add_u64 v[64:65], s[2:3], 0, v[64:65]
	v_cvt_pk_bf16_f32 v71, v66, v67
	global_store_dwordx4 v[76:77], v[68:71], off offset:256 sc1
	v_cvt_pk_bf16_f32 v60, v60, v61
	v_cvt_pk_bf16_f32 v61, v62, v63
	v_cvt_pk_bf16_f32 v62, v56, v57
	v_lshl_add_u64 v[56:57], v[64:65], 0, s[18:19]
	v_lshl_add_u64 v[56:57], v[56:57], 0, s[4:5]
	v_lshl_add_u64 v[56:57], v[56:57], 0, v[136:137]
	v_cvt_pk_bf16_f32 v63, v58, v59
	global_store_dwordx4 v[56:57], v[60:63], off sc1
	v_cvt_pk_bf16_f32 v48, v48, v49
	v_cvt_pk_bf16_f32 v49, v50, v51
	v_cvt_pk_bf16_f32 v50, v40, v41
	v_add_u32_e32 v40, s13, v148
	v_ashrrev_i32_e32 v41, 31, v40
	v_lshlrev_b64 v[40:41], 11, v[40:41]
	v_cvt_pk_bf16_f32 v51, v42, v43
	global_store_dwordx4 v[56:57], v[48:51], off offset:256 sc1
	s_nop 1
	v_lshl_add_u64 v[48:49], s[2:3], 0, v[40:41]
	v_cvt_pk_bf16_f32 v40, v52, v53
	v_cvt_pk_bf16_f32 v41, v54, v55
	v_cvt_pk_bf16_f32 v42, v44, v45
	v_lshl_add_u64 v[44:45], v[48:49], 0, s[18:19]
	v_lshl_add_u64 v[44:45], v[44:45], 0, s[4:5]
	v_lshl_add_u64 v[44:45], v[44:45], 0, v[136:137]
	v_cvt_pk_bf16_f32 v43, v46, v47
	global_store_dwordx4 v[44:45], v[40:43], off sc1
	v_cvt_pk_bf16_f32 v32, v32, v33
	v_cvt_pk_bf16_f32 v33, v34, v35
	v_cvt_pk_bf16_f32 v34, v24, v25
	v_add_u32_e32 v24, s13, v149
	v_ashrrev_i32_e32 v25, 31, v24
	v_lshlrev_b64 v[24:25], 11, v[24:25]
	v_cvt_pk_bf16_f32 v35, v26, v27
	global_store_dwordx4 v[44:45], v[32:35], off offset:256 sc1
	s_nop 1
	v_lshl_add_u64 v[32:33], s[2:3], 0, v[24:25]
	v_cvt_pk_bf16_f32 v24, v36, v37
	v_cvt_pk_bf16_f32 v25, v38, v39
	v_cvt_pk_bf16_f32 v26, v28, v29
	v_lshl_add_u64 v[28:29], v[32:33], 0, s[18:19]
	v_lshl_add_u64 v[28:29], v[28:29], 0, s[4:5]
	v_lshl_add_u64 v[28:29], v[28:29], 0, v[136:137]
	v_cvt_pk_bf16_f32 v27, v30, v31
	global_store_dwordx4 v[28:29], v[24:27], off sc1
	v_cvt_pk_bf16_f32 v16, v16, v17
	v_cvt_pk_bf16_f32 v17, v18, v19
	v_cvt_pk_bf16_f32 v18, v8, v9
	v_add_u32_e32 v8, s13, v150
	v_ashrrev_i32_e32 v9, 31, v8
	v_lshlrev_b64 v[8:9], 11, v[8:9]
	v_cvt_pk_bf16_f32 v19, v10, v11
	global_store_dwordx4 v[28:29], v[16:19], off offset:256 sc1
	s_nop 1
	v_lshl_add_u64 v[16:17], s[2:3], 0, v[8:9]
	v_cvt_pk_bf16_f32 v8, v20, v21
	v_cvt_pk_bf16_f32 v9, v22, v23
	v_cvt_pk_bf16_f32 v10, v12, v13
	v_lshl_add_u64 v[12:13], v[16:17], 0, s[18:19]
	v_lshl_add_u64 v[12:13], v[12:13], 0, s[4:5]
	v_lshl_add_u64 v[12:13], v[12:13], 0, v[136:137]
	v_cvt_pk_bf16_f32 v11, v14, v15
	global_store_dwordx4 v[12:13], v[8:11], off sc1
	v_cvt_pk_bf16_f32 v4, v4, v5
	v_cvt_pk_bf16_f32 v5, v6, v7
	v_cvt_pk_bf16_f32 v6, v0, v1
	v_cvt_pk_bf16_f32 v7, v2, v3
	global_store_dwordx4 v[12:13], v[4:7], off offset:256 sc1
	s_cbranch_vccnz .LBB0_1425
	s_andn2_b64 vcc, exec, s[6:7]
	s_cbranch_vccnz .LBB0_1424
	s_barrier
	s_branch .LBB0_1424
